# v22 + static s_setprio 1 for waves 4-7 during the windowed (SWA) attention phase
# baseline (speedup 1.0000x reference)
.LBB0_1338:
	s_abs_i32 s0, s33
	v_cvt_f32_u32_e32 v1, s0
	s_sub_i32 s5, 0, s0
	s_add_i32 s1, s33, 0x3ff
	s_xor_b32 s4, s1, s33
	v_rcp_iflag_f32_e32 v1, v1
	s_abs_i32 s1, s1
	s_ashr_i32 s4, s4, 31
	v_mul_f32_e32 v1, 0x4f7ffffe, v1
	v_cvt_u32_f32_e32 v1, v1
	s_nop 0
	v_readfirstlane_b32 s6, v1
	s_mul_i32 s5, s5, s6
	s_mul_hi_u32 s5, s6, s5
	s_add_i32 s6, s6, s5
	s_mul_hi_u32 s5, s1, s6
	s_mul_i32 s6, s5, s0
	s_sub_i32 s1, s1, s6
	s_add_i32 s7, s5, 1
	s_sub_i32 s6, s1, s0
	s_cmp_ge_u32 s1, s0
	s_cselect_b32 s5, s7, s5
	s_cselect_b32 s1, s6, s1
	s_add_i32 s6, s5, 1
	s_cmp_ge_u32 s1, s0
	s_cselect_b32 s0, s6, s5
	s_xor_b32 s0, s0, s4
	s_sub_i32 s0, s0, s4
	s_mul_i32 s52, s0, s87
	s_sub_i32 s1, 0x400, s52
	s_min_i32 s0, s1, s0
	s_cmpk_lt_i32 s52, 0x400
	s_cselect_b32 s53, s0, 0
	s_cmp_lt_i32 s53, 1
	s_mov_b32 s1, 0
	s_cbranch_scc1 .LBB0_1409
	v_writelane_b32 v244, s30, 7
	s_and_b32 s0, s52, 31
	s_bfe_u32 s91, s52, 0x10005
	v_writelane_b32 v244, s31, 8
	s_min_u32 s39, s0, 29
	s_lshl_b32 s8, s91, 8
	s_lshl_b32 s4, s91, 9
	v_readlane_b32 s6, v244, 48
	v_readlane_b32 s7, v244, 49
	s_add_u32 s6, s6, s4
	s_addc_u32 s7, s7, 0
	s_ashr_i32 s4, s52, 6
	s_ashr_i32 s5, s4, 31
	v_sub_u32_e64 v1, s0, 2 clamp
	s_lshl_b64 s[12:13], s[4:5], 11
	v_readfirstlane_b32 s82, v1
	s_lshl_b64 s[4:5], s[4:5], 19
	v_lshlrev_b32_e32 v1, 14, v1
	v_or_b32_e32 v2, s4, v1
	v_mov_b32_e32 v3, s5
	v_readlane_b32 s4, v244, 52
	v_readlane_b32 s5, v244, 53
	s_lshl_b32 s9, s0, 6
	s_lshl_b32 s0, s91, 7
	v_lshl_add_u64 v[4:5], s[4:5], 0, v[2:3]
	v_readlane_b32 s4, v244, 50
	v_readlane_b32 s5, v244, 51
	v_mov_b32_e32 v7, v0
	v_lshl_add_u64 v[4:5], v[4:5], 0, s[0:1]
	v_lshl_add_u64 v[2:3], s[4:5], 0, v[2:3]
	v_lshl_add_u64 v[2:3], v[2:3], 0, s[0:1]
	s_or_b32 s22, s12, s9
	v_readfirstlane_b32 s0, v7
	s_ashr_i32 s23, s0, 6
	s_and_b32 s92, s23, 3
	s_ashr_i32 s24, s0, 3
	s_and_b32 s4, s24, 0xffffffe0
	s_and_b32 s26, s0, 0x3fffffc0
	s_lshl_b32 s0, s92, 11
	v_bfe_u32 v13, v7, 2, 4
	s_add_i32 s0, s0, s4
	s_lshl_b32 s78, s91, 6
	v_bfe_u32 v1, v7, 4, 2
	v_lshl_add_u32 v14, v13, 7, s0
	s_lshl_b32 s0, s23, 10
	v_bitop3_b32 v12, v1, v7, 3 bitop3:0x78
	s_cmp_lg_u32 0, -1
	v_and_b32_e32 v11, 3, v7
	v_lshlrev_b32_e32 v6, 3, v12
	s_cselect_b32 s5, 0, 0
	v_or_b32_e32 v1, v14, v6
	v_lshlrev_b32_e32 v11, 3, v11
	s_add_i32 s93, s0, s5
	v_readfirstlane_b32 s15, v3
	v_readfirstlane_b32 s14, v2
	s_ashr_i32 s5, s4, 31
	v_or_b32_e32 v2, s22, v13
	v_mov_b32_e32 v3, s13
	v_lshlrev_b32_e32 v1, 1, v1
	v_or_b32_e32 v14, v14, v11
	s_nop 4
	s_mov_b32 s0, m0
	s_mov_b32 m0, s93
	s_nop 0
	global_load_lds_dwordx4 v1, s[14:15]
	s_mov_b32 m0, s0
	v_lshl_add_u64 v[2:3], v[2:3], 0, s[4:5]
	s_waitcnt lgkmcnt(0)
	v_lshlrev_b32_e32 v196, 1, v14
	s_add_i32 s94, s93, 0x6000
	v_readfirstlane_b32 s15, v5
	v_readfirstlane_b32 s14, v4
	s_nop 4
	s_mov_b32 s0, m0
	s_mov_b32 m0, s94
	s_nop 0
	global_load_lds_dwordx4 v196, s[14:15]
	s_mov_b32 m0, s0
	v_lshlrev_b64 v[2:3], 10, v[2:3]
	v_lshl_add_u64 v[2:3], s[6:7], 0, v[2:3]
	s_lshl_b32 s0, s92, 7
	v_lshl_add_u64 v[2:3], v[2:3], 0, s[0:1]
	v_mov_b32_e32 v179, 0
	v_lshlrev_b32_e32 v178, 4, v12
	v_lshl_add_u64 v[2:3], v[2:3], 0, v[178:179]
	s_movk_i32 s0, 0x4000
	v_add_co_u32_e32 v4, vcc, s0, v2
	s_mul_i32 s27, s23, 0x1800
	s_nop 0
	v_addc_co_u32_e32 v5, vcc, 0, v3, vcc
	global_load_dwordx4 v[130:133], v[2:3], off
	global_load_dwordx4 v[134:137], v[2:3], off offset:64
	global_load_dwordx4 v[138:141], v[4:5], off
	global_load_dwordx4 v[142:145], v[4:5], off offset:64
	s_lshl_b32 s0, s26, 2
	v_mov_b32_e32 v181, s5
	s_lshl_b32 s5, s23, 12
	v_and_b32_e32 v9, 31, v7
	v_bfe_u32 v10, v7, 5, 1
	v_lshlrev_b32_e32 v14, 6, v7
	s_add_i32 s0, s0, 0
	s_add_i32 s6, s27, 0
	s_add_i32 s5, s5, 0
	v_and_b32_e32 v8, 63, v7
	v_and_b32_e32 v15, 0x400, v14
	v_and_b32_e32 v14, 0x3c0, v14
	v_lshlrev_b32_e32 v16, 1, v7
	v_lshlrev_b32_e32 v17, 2, v10
	v_lshrrev_b32_e32 v18, 2, v7
	v_bfe_u32 v19, v7, 2, 2
	s_add_i32 s14, s6, 0x12800
	v_lshl_add_u32 v202, v9, 2, s0
	v_lshl_add_u32 v5, v9, 1, s5
	v_bfe_u32 v9, v7, 3, 3
	v_and_b32_e32 v16, 32, v16
	v_or_b32_e32 v19, v17, v19
	v_bitop3_b32 v18, v10, v18, 3 bitop3:0x78
	v_add3_u32 v197, 0, v15, v14
	v_cmp_gt_u32_e64 s[6:7], 32, v8
	v_lshlrev_b32_e32 v3, 4, v8
	v_add3_u32 v201, s14, v15, v14
	v_or_b32_e32 v180, s4, v13
	v_lshlrev_b32_e32 v2, 3, v7
	v_lshlrev_b32_e32 v13, 7, v9
	v_lshl_add_u32 v204, v10, 4, s0
	v_lshlrev_b32_e32 v14, 9, v10
	v_lshlrev_b32_e32 v4, 10, v9
	v_or_b32_e32 v8, 8, v9
	v_or_b32_e32 v10, 16, v9
	v_or_b32_e32 v9, 24, v9
	s_movk_i32 s25, 0xffe0
	v_add_u32_e32 v16, 0, v16
	v_lshlrev_b32_e32 v19, 6, v19
	v_lshlrev_b32_e32 v199, 4, v18
	v_and_b32_e32 v2, 56, v2
	v_lshlrev_b32_e32 v18, 7, v9
	v_lshlrev_b32_e32 v12, 10, v9
	v_mov_b32_e32 v9, s24
	s_lshl_b32 s38, s92, 6
	v_add3_u32 v198, v16, v11, v19
	v_lshl_add_u32 v11, v2, 1, s5
	v_lshlrev_b32_e32 v15, 7, v8
	v_lshlrev_b32_e32 v8, 10, v8
	v_lshlrev_b32_e32 v16, 7, v10
	v_lshlrev_b32_e32 v10, 10, v10
	v_bfi_b32 v7, s25, v9, v7
	v_add_u32_e32 v206, s14, v3
	s_mov_b32 s14, 2.0
	s_mov_b32 s36, 0x41000000
	s_mov_b32 s40, 0x41200000
	s_mov_b32 s54, 0x41800000
	s_mov_b32 s56, 0x41900000
	s_mov_b32 s42, 0x41c00000
	s_mov_b32 s44, 0x41d00000
	s_mov_b32 s46, 0x42080000
	s_mov_b32 s48, 0x42200000
	s_mov_b32 s50, 0x42280000
	s_mov_b32 s58, 0x42400000
	s_mov_b32 s60, 0x42480000
	s_mov_b32 s62, 0x42600000
	s_mov_b32 s64, 0x42680000
	v_cndmask_b32_e64 v200, 0, 1.0, s[6:7]
	v_xor_b32_e32 v203, 32, v199
	v_sub_u32_e32 v205, v7, v17
	s_sub_i32 s5, 0, s4
	s_mov_b32 s15, 0x40400000
	s_mov_b32 s37, 0x41100000
	s_mov_b32 s41, 0x41300000
	s_mov_b32 s55, 0x41880000
	s_mov_b32 s57, 0x41980000
	s_mov_b32 s43, 0x41c80000
	s_mov_b32 s45, 0x41d80000
	s_mov_b32 s95, 0x43000000
	s_mov_b32 s47, 0x420c0000
	s_mov_b32 s49, 0x42240000
	s_mov_b32 s51, 0x422c0000
	s_mov_b32 s59, 0x42440000
	s_mov_b32 s61, 0x424c0000
	s_mov_b32 s63, 0x42640000
	s_mov_b32 s65, 0x426c0000
	v_lshlrev_b32_e32 v182, 1, v6
	v_add_u32_e32 v207, v5, v14
	s_lshl_b32 s66, s38, 1
	v_lshlrev_b32_e32 v178, 1, v2
	v_add_u32_e32 v208, v11, v13
	v_lshlrev_b32_e32 v184, 1, v4
	v_add_u32_e32 v209, v11, v15
	v_lshlrev_b32_e32 v186, 1, v8
	v_add_u32_e32 v210, v11, v16
	v_lshlrev_b32_e32 v188, 1, v10
	v_add_u32_e32 v211, v11, v18
	v_lshlrev_b32_e32 v190, 1, v12
	v_mov_b32_e32 v212, 0xff800000
	s_mov_b32 s96, 0
	s_mov_b32 s97, 0
	v_readfirstlane_b32 s100, v0
	s_nop 0
	s_cmp_lt_u32 s100, 0x100
	s_cbranch_scc1 .Lswa_noprio
	s_setprio 1
.Lswa_noprio:
	s_branch .LBB0_1341
.LBB0_1340:
	s_or_b64 exec, exec, s[70:71]
	ds_read_b128 v[2:5], v204 offset:41088
	ds_read_b128 v[6:9], v204 offset:41120
	s_add_i32 s0, s9, s4
	s_min_u32 s39, s38, 29
	s_ashr_i32 s9, s0, 31
	s_waitcnt lgkmcnt(1)
	v_rcp_f32_e32 v10, v2
	v_rcp_f32_e32 v11, v3
	v_rcp_f32_e32 v12, v4
	v_rcp_f32_e32 v13, v5
	v_mul_f32_e32 v18, v34, v10
	v_mul_f32_e32 v10, v50, v10
	v_cvt_pk_bf16_f32 v10, v10, s0
	ds_write_b16 v207, v10 offset:43072
	v_mul_f32_e32 v10, v35, v11
	v_cvt_pk_bf16_f32 v10, v10, s0
	ds_write_b16 v207, v10 offset:43136
	v_mul_f32_e32 v10, v51, v11
	v_cvt_pk_bf16_f32 v10, v10, s0
	ds_write_b16 v207, v10 offset:43200
	v_mul_f32_e32 v10, v36, v12
	v_cvt_pk_bf16_f32 v10, v10, s0
	ds_write_b16 v207, v10 offset:43264
	v_mul_f32_e32 v10, v52, v12
	v_cvt_pk_bf16_f32 v10, v10, s0
	s_waitcnt lgkmcnt(4)
	v_rcp_f32_e32 v14, v6
	ds_write_b16 v207, v10 offset:43328
	v_mul_f32_e32 v10, v37, v13
	v_cvt_pk_bf16_f32 v10, v10, s0
	ds_write_b16 v207, v10 offset:43392
	v_mul_f32_e32 v10, v53, v13
	v_cvt_pk_bf16_f32 v10, v10, s0
	v_rcp_f32_e32 v15, v7
	ds_write_b16 v207, v10 offset:43456
	v_mul_f32_e32 v10, v38, v14
	v_cvt_pk_bf16_f32 v10, v10, s0
	ds_write_b16 v207, v10 offset:44032
	v_mul_f32_e32 v10, v54, v14
	v_cvt_pk_bf16_f32 v10, v10, s0
	v_rcp_f32_e32 v16, v8
	ds_write_b16 v207, v10 offset:44096
	v_mul_f32_e32 v10, v39, v15
	v_cvt_pk_bf16_f32 v10, v10, s0
	ds_write_b16 v207, v10 offset:44160
	v_mul_f32_e32 v10, v55, v15
	ds_read_b128 v[2:5], v204 offset:41152
	v_cvt_pk_bf16_f32 v10, v10, s0
	v_rcp_f32_e32 v17, v9
	ds_write_b16 v207, v10 offset:44224
	v_mul_f32_e32 v10, v40, v16
	v_cvt_pk_bf16_f32 v10, v10, s0
	ds_write_b16 v207, v10 offset:44288
	v_mul_f32_e32 v10, v56, v16
	v_cvt_pk_bf16_f32 v10, v10, s0
	ds_read_b128 v[6:9], v204 offset:41184
	s_waitcnt lgkmcnt(3)
	v_rcp_f32_e32 v2, v2
	ds_write_b16 v207, v10 offset:44352
	v_mul_f32_e32 v10, v41, v17
	v_cvt_pk_bf16_f32 v10, v10, s0
	v_rcp_f32_e32 v3, v3
	ds_write_b16 v207, v10 offset:44416
	v_mul_f32_e32 v10, v57, v17
	v_cvt_pk_bf16_f32 v10, v10, s0
	ds_write_b16 v207, v10 offset:44480
	v_mul_f32_e32 v10, v42, v2
	v_mul_f32_e32 v2, v58, v2
	v_cvt_pk_bf16_f32 v2, v2, s0
	v_rcp_f32_e32 v4, v4
	ds_write_b16 v207, v2 offset:45120
	v_mul_f32_e32 v2, v43, v3
	v_cvt_pk_bf16_f32 v2, v2, s0
	ds_write_b16 v207, v2 offset:45184
	v_mul_f32_e32 v2, v59, v3
	v_cvt_pk_bf16_f32 v2, v2, s0
	v_rcp_f32_e32 v5, v5
	ds_write_b16 v207, v2 offset:45248
	v_mul_f32_e32 v2, v44, v4
	v_cvt_pk_bf16_f32 v2, v2, s0
	ds_write_b16 v207, v2 offset:45312
	v_mul_f32_e32 v2, v60, v4
	v_cvt_pk_bf16_f32 v2, v2, s0
	s_waitcnt lgkmcnt(7)
	v_rcp_f32_e32 v6, v6
	ds_write_b16 v207, v2 offset:45376
	v_mul_f32_e32 v2, v45, v5
	v_cvt_pk_bf16_f32 v2, v2, s0
	ds_write_b16 v207, v2 offset:45440
	v_mul_f32_e32 v2, v61, v5
	v_cvt_pk_bf16_f32 v2, v2, s0
	v_rcp_f32_e32 v7, v7
	ds_write_b16 v207, v2 offset:45504
	v_mul_f32_e32 v2, v46, v6
	v_cvt_pk_bf16_f32 v2, v2, s0
	ds_write_b16 v207, v2 offset:46080
	v_mul_f32_e32 v2, v62, v6
	v_cvt_pk_bf16_f32 v2, v2, s0
	v_rcp_f32_e32 v8, v8
	ds_write_b16 v207, v2 offset:46144
	v_mul_f32_e32 v2, v47, v7
	v_cvt_pk_bf16_f32 v2, v2, s0
	ds_write_b16 v207, v2 offset:46208
	v_mul_f32_e32 v2, v63, v7
	v_cvt_pk_bf16_f32 v2, v2, s0
	v_rcp_f32_e32 v9, v9
	ds_write_b16 v207, v2 offset:46272
	v_mul_f32_e32 v2, v48, v8
	v_cvt_pk_bf16_f32 v2, v2, s0
	ds_write_b16 v207, v2 offset:46336
	v_mul_f32_e32 v2, v64, v8
	v_cvt_pk_bf16_f32 v2, v2, s0
	ds_write_b16 v207, v2 offset:46400
	v_mul_f32_e32 v2, v49, v9
	s_add_u32 s12, s12, s0
	v_cvt_pk_bf16_f32 v2, v2, s0
	s_addc_u32 s13, s13, s9
	ds_write_b16 v207, v2 offset:46464
	v_mul_f32_e32 v2, v65, v9
	s_lshl_b64 s[12:13], s[12:13], 11
	v_cvt_pk_bf16_f32 v18, v18, s0
	v_cvt_pk_bf16_f32 v10, v10, s0
	v_cvt_pk_bf16_f32 v2, v2, s0
	s_add_u32 s0, s3, s12
	s_mov_b32 s9, s1
	s_addc_u32 s12, s90, s13
	s_lshl_b64 s[8:9], s[8:9], 1
	ds_write_b16 v207, v18 offset:43008
	s_add_u32 s0, s0, s8
	ds_write_b16 v207, v2 offset:46528
	s_addc_u32 s9, s12, s9
	ds_read_b128 v[2:5], v208 offset:43008
	ds_read_b128 v[6:9], v209 offset:43008
	s_add_u32 s8, s0, s66
	s_addc_u32 s9, s9, 0
	ds_write_b16 v207, v10 offset:45056
	v_lshl_add_u64 v[10:11], s[8:9], 0, v[178:179]
	v_mov_b32_e32 v185, v179
	v_lshl_add_u64 v[12:13], v[10:11], 0, v[184:185]
	v_mov_b32_e32 v187, v179
	s_waitcnt lgkmcnt(2)
	global_store_dwordx4 v[12:13], v[2:5], off offset:1024
	v_lshl_add_u64 v[12:13], v[10:11], 0, v[186:187]
	ds_read_b128 v[2:5], v210 offset:43008
	s_waitcnt lgkmcnt(2)
	global_store_dwordx4 v[12:13], v[6:9], off offset:1024
	ds_read_b128 v[6:9], v211 offset:43008
	v_mov_b32_e32 v189, v179
	v_lshl_add_u64 v[12:13], v[10:11], 0, v[188:189]
	v_mov_b32_e32 v191, v179
	s_waitcnt lgkmcnt(1)
	global_store_dwordx4 v[12:13], v[2:5], off offset:1024
	s_cmp_lg_u32 s97, s53
	s_mov_b32 s78, s68
	v_lshl_add_u64 v[2:3], v[10:11], 0, v[190:191]
	s_mov_b32 s8, s75
	s_mov_b32 s82, s69
	s_mov_b32 s9, s74
	s_mov_b64 s[12:13], s[72:73]
	s_waitcnt lgkmcnt(0)
	global_store_dwordx4 v[2:3], v[6:9], off offset:1024
	s_cbranch_scc0 .LBB0_1408

.LBB0_1408:
	s_waitcnt vmcnt(0) lgkmcnt(0)
	s_barrier
	s_setprio 0
	v_readlane_b32 s94, v244, 62
	v_readlane_b32 s30, v244, 7
	v_readlane_b32 s95, v244, 63
	v_readlane_b32 s31, v244, 8
